# windowed attention: skip reloading the bias LUT into LDS when the previous unit on this CU used the same kv head (tag in an SGPR, invalidated by global units)
# speedup vs baseline: 1.0050x; 1.0050x over previous
; __device__ __forceinline__ CArgs argp() { CArgs p = (CArgs)__builtin_amdgcn_kernarg_segment_ptr(); asm volatile("" : "+s"(p)); return p; }
; __global__ void __launch_bounds__(NWAVES * 64, 2) mega_fwd(Args a_unused) {
;     ...
;             const Ids I = ids(bst); CArgs ap = argp(); unsigned char* ws = ap->ws;
;             const bf16* PROJ = (const bf16*)(ws + WS_PROJ); const bf16* VT = (const bf16*)(ws + WS_VT); bf16* AO = (bf16*)ap->out;   const float* lutg = (const float*)(ws + WS_LUT);
;             const float* sinkp = ap->in[5] + l * 8;
;             float gq = fabsf(ap->in[6][l * 64 + I.lane]), gk = fabsf(ap->in[7][l * 64 + I.lane]);
; #pragma unroll
;             for (int o_ = 1; o_ < 64; o_ <<= 1) { gq = fmaxf(gq, __shfl_xor(gq, o_)); gk = fmaxf(gk, __shfl_xor(gk, o_)); }
;             const float bound2 = 64.0f * QSCALE_F * gq * gk * 1.01f;
;             if (bound2 <= 100.0f) {
; #pragma unroll 1
;             for (int rep_ = 0; rep_ < DUP_ATT; ++rep_)
; #pragma unroll 1
;             for (int u = I.vcu; u < 4096; u += I.G) {
;                 const int kind = u >> 10, idx = u & 1023; const bool sample = kind & 1, win = kind >= 2;
;                 const int S = sample ? 8192 : 4096, nqb = S >> 8, per = 4 * nqb;
;                 const int bk = idx / per, rem = idx % per, b = bk >> 1, kvh = bk & 1, hq = kvh * 4 + rem / nqb, qb = rem % nqb;
;                 const int rowbase = (sample ? MHALF : 0) + b * S;
;                 if (win) att::attn_win(lds, PROJ, VT, AO, rowbase, S, kvh, rem * 64, lutg, sinkp);
.LBB0_197:
	s_cmp_ge_i32 s14, s33
	s_cselect_b64 s[2:3], -1, 0
	s_and_b64 s[4:5], s[2:3], s[4:5]
	s_andn2_b64 vcc, exec, s[4:5]
	s_cbranch_vccnz .LBB0_302
	v_mov_b32_e32 v0, v171
	s_mov_b32 s47, s94
	s_waitcnt lgkmcnt(0)
	v_mov_b32_e32 v1, s87
	ds_read_b32 v4, v1
	v_mov_b32_e32 v1, s88
	s_mov_b64 s[8:9], s[0:1]
	ds_read_b32 v1, v1
	s_load_dwordx4 s[16:19], s[8:9], 0x78
	s_mov_b32 s11, s6
	s_load_dwordx4 s[4:7], s[8:9], 0x28
	s_nop 0
	s_load_dwordx2 s[8:9], s[8:9], 0x38
	v_xor_b32_e32 v5, 2, v181
	v_xor_b32_e32 v6, 4, v181
	s_waitcnt lgkmcnt(0)
	s_add_u32 s48, s18, 0xd800000
	s_addc_u32 s49, s19, 0
	s_lshl_b32 s10, s11, 6
	v_and_or_b32 v150, v0, 63, s10
	v_lshlrev_b64 v[0:1], 2, v[150:151]
	v_lshl_add_u64 v[2:3], s[6:7], 0, v[0:1]
	global_load_dword v2, v[2:3], off
	v_lshl_add_u64 v[0:1], s[8:9], 0, v[0:1]
	global_load_dword v0, v[0:1], off
	v_and_b32_e32 v1, 64, v181
	v_xor_b32_e32 v3, 1, v181
	v_add_u32_e32 v1, 64, v1
	v_cmp_lt_i32_e32 vcc, v3, v1
	v_xor_b32_e32 v7, 8, v181
	v_xor_b32_e32 v8, 16, v181
	v_cndmask_b32_e32 v3, v181, v3, vcc
	v_cmp_lt_i32_e32 vcc, v5, v1
	v_xor_b32_e32 v9, 32, v181
	v_lshlrev_b32_e32 v3, 2, v3
	v_cndmask_b32_e32 v5, v181, v5, vcc
	v_cmp_lt_i32_e32 vcc, v6, v1
	v_lshlrev_b32_e32 v5, 2, v5
	s_lshl_b32 s14, s11, 3
	v_cndmask_b32_e32 v6, v181, v6, vcc
	v_cmp_lt_i32_e32 vcc, v7, v1
	v_lshlrev_b32_e32 v6, 2, v6
	s_add_u32 s50, s18, 0x17800000
	v_cndmask_b32_e32 v7, v181, v7, vcc
	v_cmp_lt_i32_e32 vcc, v8, v1
	v_lshlrev_b32_e32 v7, 2, v7
	s_addc_u32 s51, s19, 0
	v_cndmask_b32_e32 v8, v181, v8, vcc
	v_cmp_lt_i32_e32 vcc, v9, v1
	v_lshlrev_b32_e32 v8, 2, v8
	s_add_u32 s52, s18, 0x8000
	v_cndmask_b32_e32 v1, v181, v9, vcc
	v_lshlrev_b32_e32 v166, 2, v1
	s_addc_u32 s53, s19, 0
	s_lshl_b64 s[6:7], s[14:15], 2
	s_add_u32 s69, s4, s6
	v_readfirstlane_b32 s68, v4
	s_addc_u32 s74, s5, s7
	s_cmpk_lt_i32 s68, 0x1000
	s_cselect_b64 s[4:5], -1, 0
	s_mov_b32 s8, 0x42c80000
	v_cndmask_b32_e64 v4, 0, 1, s[4:5]
	v_cmp_ne_u32_e64 s[4:5], 1, v4
	s_waitcnt vmcnt(0)
	v_and_b32_e32 v9, 0x7fffffff, v2
	ds_bpermute_b32 v9, v3, v9
	v_and_b32_e32 v10, 0x7fffffff, v0
	ds_bpermute_b32 v3, v3, v10
	v_max_f32_e64 v2, |v2|, |v2|
	v_max_f32_e64 v0, |v0|, |v0|
	s_waitcnt lgkmcnt(1)
	v_max_f32_e32 v9, v9, v9
	v_max_f32_e32 v2, v2, v9
	s_waitcnt lgkmcnt(0)
	v_max_f32_e32 v3, v3, v3
	v_max_f32_e32 v0, v0, v3
	ds_bpermute_b32 v3, v5, v2
	ds_bpermute_b32 v5, v5, v0
	s_waitcnt lgkmcnt(1)
	v_max_f32_e32 v1, v3, v3
	s_waitcnt lgkmcnt(0)
	v_max_f32_e32 v3, v5, v5
	v_max_f32_e32 v1, v2, v1
	v_max_f32_e32 v0, v0, v3
	ds_bpermute_b32 v2, v6, v1
	ds_bpermute_b32 v3, v6, v0
	s_waitcnt lgkmcnt(1)
	v_max_f32_e32 v2, v2, v2
	s_waitcnt lgkmcnt(0)
	v_max_f32_e32 v3, v3, v3
	v_max_f32_e32 v1, v1, v2
	v_max_f32_e32 v0, v0, v3
	ds_bpermute_b32 v2, v7, v1
	ds_bpermute_b32 v3, v7, v0
	s_waitcnt lgkmcnt(1)
	v_max_f32_e32 v2, v2, v2
	s_waitcnt lgkmcnt(0)
	v_max_f32_e32 v3, v3, v3
	v_max_f32_e32 v1, v1, v2
	v_max_f32_e32 v0, v0, v3
	ds_bpermute_b32 v2, v8, v1
	ds_bpermute_b32 v3, v8, v0
	s_waitcnt lgkmcnt(1)
	v_max_f32_e32 v2, v2, v2
	s_waitcnt lgkmcnt(0)
	v_max_f32_e32 v3, v3, v3
	v_max_f32_e32 v1, v1, v2
	v_max_f32_e32 v0, v0, v3
	ds_bpermute_b32 v2, v166, v1
	ds_bpermute_b32 v3, v166, v0
	s_waitcnt lgkmcnt(1)
	v_max_f32_e32 v2, v2, v2
	s_waitcnt lgkmcnt(0)
	v_max_f32_e32 v3, v3, v3
	v_max_f32_e32 v1, v1, v2
	v_max_f32_e32 v0, v0, v3
	v_mul_f32_e32 v1, 0x4138aa3b, v1
	v_mul_f32_e32 v0, v0, v1
	v_mul_f32_e32 v0, 0x3f8147ae, v0
	v_cmp_ge_f32_e32 vcc, s8, v0
	s_and_saveexec_b64 s[6:7], vcc
	s_xor_b64 s[54:55], exec, s[6:7]
	s_cbranch_execz .LBB0_270
	s_and_b64 vcc, exec, s[4:5]
	s_cbranch_vccnz .LBB0_270
	s_add_u32 s56, s18, 0xa0000
	s_addc_u32 s57, s19, 0
	s_add_u32 s58, s18, 0x20000
	s_addc_u32 s59, s19, 0
	s_add_u32 s60, s18, 0x17810000
	s_addc_u32 s61, s19, 0
	s_add_u32 s62, s18, 0xd850800
	s_addc_u32 s63, s19, 0
	s_mov_b32 s75, s68
	s_mov_b32 s100, -1
	s_branch .LBB0_204

.LBB0_206:
	s_mov_b32 s100, -1
	s_mov_b32 s99, 0
	v_mov_b64_e32 v[158:159], v[134:135]
	v_mov_b64_e32 v[160:161], v[132:133]
	ds_read_b128 v[222:225], v186 offset:9216
	ds_read_b128 v[226:229], v186 offset:13824
	ds_read_b128 v[230:233], v186 offset:9248
	ds_read_b128 v[234:237], v186 offset:13856
	ds_read_b128 v[138:141], v186 offset:9280
	ds_read_b128 v[142:145], v186 offset:13888
	ds_read_b128 v[162:165], v186 offset:9312
	ds_read_b128 v[132:135], v186 offset:13920
	v_exp_f32_e32 v32, v32
	v_exp_f32_e32 v33, v33
	v_exp_f32_e32 v34, v34
	v_exp_f32_e32 v35, v35
	v_exp_f32_e32 v36, v36
	v_exp_f32_e32 v37, v37
	v_exp_f32_e32 v38, v38
	v_exp_f32_e32 v39, v39
	v_exp_f32_e32 v40, v40
	v_exp_f32_e32 v41, v41
	v_exp_f32_e32 v42, v42
	v_exp_f32_e32 v43, v43
	v_exp_f32_e32 v44, v44
	v_exp_f32_e32 v45, v45
	v_exp_f32_e32 v46, v46
	v_exp_f32_e32 v47, v47

; #define LAS __attribute__((address_space(3)))
; __device__ __forceinline__ void attn_win(LAS unsigned char* lds, const bf16_t* __restrict__ PROJ, const bf16_t* __restrict__ VT, bf16_t* __restrict__ AO, ...
;     ...
;     LAS float* lut4 = (LAS float*)(lds + OFF_LUT);
;     for (int i = tid; i < 4 * 452; i += 512) lut4[i] = lut_g[kvh * 4 * 452 + i];
.LBB0_252:
	v_mov_b32_e32 v0, v171
	s_movk_i32 s6, 0x710
	s_nop 0
	v_readfirstlane_b32 s13, v0
	s_cmp_eq_u32 s100, s80
	s_cbranch_scc1 .Lwin_lutskip
	v_cmp_gt_i32_e32 vcc, s6, v0
	s_and_saveexec_b64 s[6:7], vcc
	s_cbranch_execz .LBB0_260
	v_max_i32_e32 v1, 0x510, v0
	v_sub_u32_e32 v1, v1, v0
	v_add_u32_e32 v1, 0x1ff, v1
	s_movk_i32 s8, 0x1ff
	v_cmp_lt_u32_e32 vcc, s8, v1
	s_mov_b64 s[10:11], -1
	v_mov_b32_e32 v2, v0
	s_and_saveexec_b64 s[8:9], vcc
	s_cbranch_execz .LBB0_257
	v_lshrrev_b32_e32 v1, 9, v1
	v_add_u32_e32 v4, 1, v1
	s_mul_i32 s12, s80, 0x710
	v_and_b32_e32 v5, 0xfffffe, v4
	v_add_u32_e32 v1, 0x200, v0
	s_add_i32 s10, 0, 0x9000
	s_mov_b32 s14, s12
	v_lshl_add_u32 v6, v0, 2, s10
	s_mov_b64 s[10:11], 0
	v_mov_b32_e32 v7, v5
	v_mov_b64_e32 v[2:3], v[0:1]

; #define LAS __attribute__((address_space(3)))
; __device__ __forceinline__ void attn_win(LAS unsigned char* lds, const bf16_t* __restrict__ PROJ, const bf16_t* __restrict__ VT, bf16_t* __restrict__ AO, ...
;     ...
;     LAS float* lut4 = (LAS float*)(lds + OFF_LUT);
;     for (int i = tid; i < 4 * 452; i += 512) lut4[i] = lut_g[kvh * 4 * 452 + i];
;     const LAS float* lut = lut4 + (wid >> 1) * 452;
;     const float sink2 = sinkp[hq] * LOG2E_F;
;     const int qw = q0 + (wid & 1) * 32;
;     const bf16_t* qp = PROJ + (size_t)(rowbase + qw + r32) * PITCH_P + qcol + hi * 8;
;     bf16x8 qf[4];
; #pragma unroll
;     for (int ds = 0; ds < 4; ++ds) qf[ds] = *(const bf16x8*)(qp + ds * 16);
;     u32x4 kreg = *(const u32x4*)(ksrc + (size_t)kt0 * 64 * PITCH_P);
;     u32x4 vreg = *(const u32x4*)(vsrc + (size_t)kt0 * 16384);
;     *(LAS u32x4*)(lds + kdst) = kreg;
;     *(LAS u32x2*)(lds + vdst) = (u32x2){vreg.x, vreg.y}; *(LAS u32x2*)(lds + vdst + 16) = (u32x2){vreg.z, vreg.w};
;     if (kt0 + 1 < kt1) { kreg = *(const u32x4*)(ksrc + (size_t)(kt0 + 1) * 64 * PITCH_P); vreg = *(const u32x4*)(vsrc + (size_t)(kt0 + 1) * 16384); }
.LBB0_260:
	s_or_b64 exec, exec, s[6:7]
	s_mov_b32 s100, s80
.Lwin_lutskip:
	s_lshl_b32 s30, s81, 6
	s_add_i32 s7, s30, 0xc0
	s_lshl_b32 s6, s80, 2
	s_ashr_i32 s11, s13, 7
	s_min_u32 s7, s7, s79
	v_ashrrev_i32_e32 v2, 3, v0
	s_add_i32 s64, s11, s6
	v_sub_u32_e64 v16, s30, v184 clamp
	s_lshr_b32 s9, s7, 6
	v_add_u32_e32 v3, s78, v2
	v_mov_b64_e32 v[6:7], s[48:49]
	s_lshl_b32 s7, s78, 2
	s_lshl_b32 s31, s80, 6
	v_readfirstlane_b32 s8, v16
	v_mad_i64_i32 v[4:5], s[66:67], v3, s92, v[6:7]
	s_and_b32 s7, s7, 0x7c000
	s_ashr_i32 s65, s64, 31
	s_lshl_b32 s6, s64, 6
	s_lshr_b32 s8, s8, 6
	s_lshl_b32 s14, s80, 7
	s_or_b32 s66, s7, s31
	s_lshl_b64 s[64:65], s[64:65], 2
	s_add_u32 s64, s69, s64
	s_mov_b32 s67, s15
	v_ashrrev_i32_e32 v3, 31, v2
	s_addc_u32 s65, s74, s65
	s_lshr_b32 s7, s13, 1
	v_and_b32_e32 v1, 31, v0
	v_lshlrev_b32_e32 v17, 4, v0
	v_lshl_add_u64 v[10:11], v[2:3], 0, s[66:67]
	s_and_b32 s7, s7, 32
	v_lshl_add_u64 v[8:9], v[4:5], 0, s[14:15]
	v_and_b32_e32 v4, 0x70, v17
	v_mov_b32_e32 v5, v151
	v_lshlrev_b64 v[10:11], 7, v[10:11]
	s_or_b32 s12, s7, s30
	v_or_b32_e32 v12, s78, v1
	v_lshl_add_u64 v[8:9], v[8:9], 0, v[4:5]
	v_lshl_add_u64 v[10:11], s[50:51], 0, v[10:11]
	v_add_u32_e32 v150, s12, v12
	v_bfe_u32 v167, v0, 5, 1
	v_lshl_add_u64 v[10:11], v[10:11], 0, v[4:5]
	global_load_dword v5, v151, s[64:65]
	v_mad_u64_u32 v[6:7], s[64:65], v150, s92, v[6:7]
	s_ashr_i32 s7, s6, 31
	v_mad_u64_u32 v[14:15], s[64:65], s8, v185, v[8:9]
	v_lshl_add_u64 v[12:13], s[6:7], 1, v[6:7]
	v_lshlrev_b32_e32 v6, 4, v167
	v_mov_b32_e32 v7, v151
	s_lshl_b32 s64, s8, 15
	s_mov_b32 s65, s15
	v_lshl_add_u64 v[12:13], v[12:13], 0, v[6:7]
	global_load_dwordx4 v[76:79], v[14:15], off offset:2048
	global_load_dwordx4 v[64:67], v[12:13], off
	global_load_dwordx4 v[68:71], v[12:13], off offset:32
	v_lshl_add_u64 v[14:15], v[10:11], 0, s[64:65]
	global_load_dwordx4 v[84:87], v[14:15], off
	global_load_dwordx4 v[72:75], v[12:13], off offset:64
	global_load_dwordx4 v[80:83], v[12:13], off offset:96
	s_movk_i32 s10, 0x90
	v_lshlrev_b32_e32 v0, 3, v0
	v_mul_lo_u32 v7, v2, s10
	v_and_b32_e32 v12, 0x60, v17
	v_and_or_b32 v0, v0, 8, v7
	v_add_u32_e32 v93, v0, v12
	v_add_u32_e32 v92, v7, v4
	v_add_u32_e32 v0, 0, v93
	s_add_i32 s64, s8, 1
	v_readfirstlane_b32 s10, v16
	v_add_u32_e32 v7, 0, v92
	v_add_u32_e32 v0, 0x4800, v0
	s_cmp_lt_u32 s64, s9
	s_waitcnt vmcnt(5)
	ds_write_b128 v7, v[76:79]
	s_waitcnt vmcnt(2)
	ds_write2_b64 v0, v[84:85], v[86:87] offset1:2
	s_cbranch_scc0 .LBB0_262
	v_mad_u64_u32 v[8:9], s[66:67], s64, v185, v[8:9]
	s_lshl_b32 s64, s64, 15
	s_mov_b32 s65, s15
	v_lshl_add_u64 v[10:11], v[10:11], 0, s[64:65]
	global_load_dwordx4 v[76:79], v[8:9], off offset:2048
	global_load_dwordx4 v[84:87], v[10:11], off
